# EpiY epilogue (SSM Y GEMM) rewritten: packed-f32 gelu argument, n0/n1 quads paired, 16-byte stores via SGPR base
# speedup vs baseline: 1.0019x; 1.0019x over previous
; __device__ __forceinline__ unsigned cvt_pk_bf16(float lo, float hi) { unsigned r; asm("v_cvt_pk_bf16_f32 %0, %1, %2" : "=v"(r) : "v"(lo), "v"(hi)); return r; }
; __device__ __forceinline__ float gelu_tanh(float x) { const float u = 0.7978845608028654f * (x + 0.044715f * x * x * x); return x * fast_sigmoid(2.0f * u); }
; __device__ __forceinline__ float fast_sigmoid(float x) { return __builtin_amdgcn_rcpf(1.0f + __builtin_amdgcn_exp2f(-x * LOG2E)); }
;     __device__ __forceinline__ void operator()(const Acc& acc, const Unit& u, int wr, int wc, int fr, int fq) const {
;     ...
;             for (int m = 0; m < 4; ++m) { const int nrow = pml * 256 + ai * 128 + wr * 64 + m * 16 + fr;
; #pragma unroll
;                 for (int bj = 0; bj < 2; ++bj)
; #pragma unroll
;                     for (int n = 0; n < 2; ++n) { const int t = pnl * 16 + bj * 8 + wc * 2 + n; const f32x4 a = acc[ai][bj][m][n];
;                         u32x2 w; w.x = cvt_pk_bf16(gelu_tanh(a[0]), gelu_tanh(a[1])); w.y = cvt_pk_bf16(gelu_tanh(a[2]), gelu_tanh(a[3]));
;                         *(u32x2*)(G + ((size_t)g * MX + nrow * 32 + t) * 16 + 4 * fq) = w; } }
.LBB0_769:
	s_mul_hi_i32 s40, s34, 0x66666667
	s_lshr_b32 s41, s40, 31
	s_ashr_i32 s40, s40, 1
	s_add_i32 s40, s40, s41
	s_mul_i32 s41, s40, 5
	s_sub_i32 s42, s34, s41
	s_lshl_b32 s40, s40, 15
	s_lshl_b32 s42, s42, 13
	s_add_i32 s40, s40, s42
	s_lshl_b32 s34, s35, 4
	s_and_b32 s34, s34, 16
	s_or_b32 s34, s34, s56
	s_or_b32 s40, s40, s34
	s_lshl_b32 s40, s40, 5
	v_bfe_u32 v149, v206, 4, 2
	v_and_b32_e32 v152, 1, v149
	v_mul_u32_u24_e32 v152, 24, v152
	v_lshl_add_u32 v152, v149, 3, v152
	v_lshl_add_u32 v152, v145, 5, v152
	v_add_u32_e32 v152, s40, v152
	v_readfirstlane_b32 s34, v132
	v_readfirstlane_b32 s35, v133
	s_mov_b32 s40, 0x3d372713
	s_mov_b32 s41, 0x3d372713
	s_mov_b32 s42, 0xc0135761
	s_mov_b32 s43, 0xc0135761
	v_pk_mul_f32 v[142:143], v[124:125], v[124:125]
	v_pk_mul_f32 v[150:151], v[126:127], v[126:127]
	v_pk_fma_f32 v[142:143], v[142:143], s[40:41], 1.0 op_sel_hi:[1,1,0]
	v_pk_fma_f32 v[150:151], v[150:151], s[40:41], 1.0 op_sel_hi:[1,1,0]
	v_pk_mul_f32 v[142:143], v[142:143], s[42:43]
	v_pk_mul_f32 v[150:151], v[150:151], s[42:43]
	v_pk_mul_f32 v[142:143], v[142:143], v[124:125]
	v_pk_mul_f32 v[150:151], v[150:151], v[126:127]
	v_exp_f32_e32 v142, v142
	v_exp_f32_e32 v143, v143
	v_exp_f32_e32 v150, v150
	v_exp_f32_e32 v151, v151
	v_pk_add_f32 v[142:143], v[142:143], 1.0 op_sel_hi:[1,0]
	v_pk_add_f32 v[150:151], v[150:151], 1.0 op_sel_hi:[1,0]
	v_rcp_f32_e32 v142, v142
	v_rcp_f32_e32 v143, v143
	v_rcp_f32_e32 v150, v150
	v_rcp_f32_e32 v151, v151
	v_pk_mul_f32 v[124:125], v[124:125], v[142:143]
	v_pk_mul_f32 v[126:127], v[126:127], v[150:151]
	v_pk_mul_f32 v[142:143], v[120:121], v[120:121]
	v_pk_mul_f32 v[150:151], v[122:123], v[122:123]
	v_pk_fma_f32 v[142:143], v[142:143], s[40:41], 1.0 op_sel_hi:[1,1,0]
	v_pk_fma_f32 v[150:151], v[150:151], s[40:41], 1.0 op_sel_hi:[1,1,0]
	v_pk_mul_f32 v[142:143], v[142:143], s[42:43]
	v_pk_mul_f32 v[150:151], v[150:151], s[42:43]
	v_pk_mul_f32 v[142:143], v[142:143], v[120:121]
	v_pk_mul_f32 v[150:151], v[150:151], v[122:123]
	v_exp_f32_e32 v142, v142
	v_exp_f32_e32 v143, v143
	v_exp_f32_e32 v150, v150
	v_exp_f32_e32 v151, v151
	v_pk_add_f32 v[142:143], v[142:143], 1.0 op_sel_hi:[1,0]
	v_pk_add_f32 v[150:151], v[150:151], 1.0 op_sel_hi:[1,0]
	v_rcp_f32_e32 v142, v142
	v_rcp_f32_e32 v143, v143
	v_rcp_f32_e32 v150, v150
	v_rcp_f32_e32 v151, v151
	v_pk_mul_f32 v[120:121], v[120:121], v[142:143]
	v_pk_mul_f32 v[122:123], v[122:123], v[150:151]
	v_cvt_pk_bf16_f32 v124, v124, v125
	v_cvt_pk_bf16_f32 v125, v126, v127
	v_cvt_pk_bf16_f32 v126, v120, v121
	v_cvt_pk_bf16_f32 v127, v122, v123
	s_nop 1
	v_permlane16_swap_b32_e32 v124, v126
	v_permlane16_swap_b32_e32 v125, v127
	global_store_dwordx4 v152, v[124:127], s[34:35]
	v_pk_mul_f32 v[142:143], v[116:117], v[116:117]
	v_pk_mul_f32 v[150:151], v[118:119], v[118:119]
	v_pk_fma_f32 v[142:143], v[142:143], s[40:41], 1.0 op_sel_hi:[1,1,0]
	v_pk_fma_f32 v[150:151], v[150:151], s[40:41], 1.0 op_sel_hi:[1,1,0]
	v_pk_mul_f32 v[142:143], v[142:143], s[42:43]
	v_pk_mul_f32 v[150:151], v[150:151], s[42:43]
	v_pk_mul_f32 v[142:143], v[142:143], v[116:117]
	v_pk_mul_f32 v[150:151], v[150:151], v[118:119]
	v_exp_f32_e32 v142, v142
	v_exp_f32_e32 v143, v143
	v_exp_f32_e32 v150, v150
	v_exp_f32_e32 v151, v151
	v_pk_add_f32 v[142:143], v[142:143], 1.0 op_sel_hi:[1,0]
	v_pk_add_f32 v[150:151], v[150:151], 1.0 op_sel_hi:[1,0]
	v_rcp_f32_e32 v142, v142
	v_rcp_f32_e32 v143, v143
	v_rcp_f32_e32 v150, v150
	v_rcp_f32_e32 v151, v151
	v_pk_mul_f32 v[116:117], v[116:117], v[142:143]
	v_pk_mul_f32 v[118:119], v[118:119], v[150:151]
	v_pk_mul_f32 v[142:143], v[112:113], v[112:113]
	v_pk_mul_f32 v[150:151], v[114:115], v[114:115]
	v_pk_fma_f32 v[142:143], v[142:143], s[40:41], 1.0 op_sel_hi:[1,1,0]
	v_pk_fma_f32 v[150:151], v[150:151], s[40:41], 1.0 op_sel_hi:[1,1,0]
	v_pk_mul_f32 v[142:143], v[142:143], s[42:43]
	v_pk_mul_f32 v[150:151], v[150:151], s[42:43]
	v_pk_mul_f32 v[142:143], v[142:143], v[112:113]
	v_pk_mul_f32 v[150:151], v[150:151], v[114:115]
	v_exp_f32_e32 v142, v142
	v_exp_f32_e32 v143, v143
	v_exp_f32_e32 v150, v150
	v_exp_f32_e32 v151, v151
	v_pk_add_f32 v[142:143], v[142:143], 1.0 op_sel_hi:[1,0]
	v_pk_add_f32 v[150:151], v[150:151], 1.0 op_sel_hi:[1,0]
	v_rcp_f32_e32 v142, v142
	v_rcp_f32_e32 v143, v143
	v_rcp_f32_e32 v150, v150
	v_rcp_f32_e32 v151, v151
	v_pk_mul_f32 v[112:113], v[112:113], v[142:143]
	v_pk_mul_f32 v[114:115], v[114:115], v[150:151]
	v_cvt_pk_bf16_f32 v116, v116, v117
	v_cvt_pk_bf16_f32 v117, v118, v119
	v_cvt_pk_bf16_f32 v118, v112, v113
	v_cvt_pk_bf16_f32 v119, v114, v115
	s_nop 1
	v_permlane16_swap_b32_e32 v116, v118
	v_permlane16_swap_b32_e32 v117, v119
	global_store_dwordx4 v152, v[116:119], s[34:35] offset:256
	v_add_u32_e32 v149, 0x4000, v152
	v_pk_mul_f32 v[142:143], v[108:109], v[108:109]
	v_pk_mul_f32 v[150:151], v[110:111], v[110:111]
	v_pk_fma_f32 v[142:143], v[142:143], s[40:41], 1.0 op_sel_hi:[1,1,0]
	v_pk_fma_f32 v[150:151], v[150:151], s[40:41], 1.0 op_sel_hi:[1,1,0]
	v_pk_mul_f32 v[142:143], v[142:143], s[42:43]
	v_pk_mul_f32 v[150:151], v[150:151], s[42:43]
	v_pk_mul_f32 v[142:143], v[142:143], v[108:109]
	v_pk_mul_f32 v[150:151], v[150:151], v[110:111]
	v_exp_f32_e32 v142, v142
	v_exp_f32_e32 v143, v143
	v_exp_f32_e32 v150, v150
	v_exp_f32_e32 v151, v151
	v_pk_add_f32 v[142:143], v[142:143], 1.0 op_sel_hi:[1,0]
	v_pk_add_f32 v[150:151], v[150:151], 1.0 op_sel_hi:[1,0]
	v_rcp_f32_e32 v142, v142
	v_rcp_f32_e32 v143, v143
	v_rcp_f32_e32 v150, v150
	v_rcp_f32_e32 v151, v151
	v_pk_mul_f32 v[108:109], v[108:109], v[142:143]
	v_pk_mul_f32 v[110:111], v[110:111], v[150:151]
	v_pk_mul_f32 v[142:143], v[104:105], v[104:105]
; __device__ __forceinline__ unsigned cvt_pk_bf16(float lo, float hi) { unsigned r; asm("v_cvt_pk_bf16_f32 %0, %1, %2" : "=v"(r) : "v"(lo), "v"(hi)); return r; }
; __device__ __forceinline__ float gelu_tanh(float x) { const float u = 0.7978845608028654f * (x + 0.044715f * x * x * x); return x * fast_sigmoid(2.0f * u); }
; __device__ __forceinline__ float fast_sigmoid(float x) { return __builtin_amdgcn_rcpf(1.0f + __builtin_amdgcn_exp2f(-x * LOG2E)); }
;     __device__ __forceinline__ void operator()(const Acc& acc, const Unit& u, int wr, int wc, int fr, int fq) const {
;     ...
;             for (int m = 0; m < 4; ++m) { const int nrow = pml * 256 + ai * 128 + wr * 64 + m * 16 + fr;
; #pragma unroll
;                 for (int bj = 0; bj < 2; ++bj)
; #pragma unroll
;                     for (int n = 0; n < 2; ++n) { const int t = pnl * 16 + bj * 8 + wc * 2 + n; const f32x4 a = acc[ai][bj][m][n];
;                         u32x2 w; w.x = cvt_pk_bf16(gelu_tanh(a[0]), gelu_tanh(a[1])); w.y = cvt_pk_bf16(gelu_tanh(a[2]), gelu_tanh(a[3]));
;                         *(u32x2*)(G + ((size_t)g * MX + nrow * 32 + t) * 16 + 4 * fq) = w; } }
	v_pk_mul_f32 v[150:151], v[106:107], v[106:107]
	v_pk_fma_f32 v[142:143], v[142:143], s[40:41], 1.0 op_sel_hi:[1,1,0]
	v_pk_fma_f32 v[150:151], v[150:151], s[40:41], 1.0 op_sel_hi:[1,1,0]
	v_pk_mul_f32 v[142:143], v[142:143], s[42:43]
	v_pk_mul_f32 v[150:151], v[150:151], s[42:43]
	v_pk_mul_f32 v[142:143], v[142:143], v[104:105]
	v_pk_mul_f32 v[150:151], v[150:151], v[106:107]
	v_exp_f32_e32 v142, v142
	v_exp_f32_e32 v143, v143
	v_exp_f32_e32 v150, v150
	v_exp_f32_e32 v151, v151
	v_pk_add_f32 v[142:143], v[142:143], 1.0 op_sel_hi:[1,0]
	v_pk_add_f32 v[150:151], v[150:151], 1.0 op_sel_hi:[1,0]
	v_rcp_f32_e32 v142, v142
	v_rcp_f32_e32 v143, v143
	v_rcp_f32_e32 v150, v150
	v_rcp_f32_e32 v151, v151
	v_pk_mul_f32 v[104:105], v[104:105], v[142:143]
	v_pk_mul_f32 v[106:107], v[106:107], v[150:151]
	v_cvt_pk_bf16_f32 v108, v108, v109
	v_cvt_pk_bf16_f32 v109, v110, v111
	v_cvt_pk_bf16_f32 v110, v104, v105
	v_cvt_pk_bf16_f32 v111, v106, v107
	s_nop 1
	v_permlane16_swap_b32_e32 v108, v110
	v_permlane16_swap_b32_e32 v109, v111
	global_store_dwordx4 v149, v[108:111], s[34:35]
	v_pk_mul_f32 v[142:143], v[100:101], v[100:101]
	v_pk_mul_f32 v[150:151], v[102:103], v[102:103]
	v_pk_fma_f32 v[142:143], v[142:143], s[40:41], 1.0 op_sel_hi:[1,1,0]
	v_pk_fma_f32 v[150:151], v[150:151], s[40:41], 1.0 op_sel_hi:[1,1,0]
	v_pk_mul_f32 v[142:143], v[142:143], s[42:43]
	v_pk_mul_f32 v[150:151], v[150:151], s[42:43]
	v_pk_mul_f32 v[142:143], v[142:143], v[100:101]
	v_pk_mul_f32 v[150:151], v[150:151], v[102:103]
	v_exp_f32_e32 v142, v142
	v_exp_f32_e32 v143, v143
	v_exp_f32_e32 v150, v150
	v_exp_f32_e32 v151, v151
	v_pk_add_f32 v[142:143], v[142:143], 1.0 op_sel_hi:[1,0]
	v_pk_add_f32 v[150:151], v[150:151], 1.0 op_sel_hi:[1,0]
	v_rcp_f32_e32 v142, v142
	v_rcp_f32_e32 v143, v143
	v_rcp_f32_e32 v150, v150
	v_rcp_f32_e32 v151, v151
	v_pk_mul_f32 v[100:101], v[100:101], v[142:143]
	v_pk_mul_f32 v[102:103], v[102:103], v[150:151]
	v_pk_mul_f32 v[142:143], v[96:97], v[96:97]
	v_pk_mul_f32 v[150:151], v[98:99], v[98:99]
	v_pk_fma_f32 v[142:143], v[142:143], s[40:41], 1.0 op_sel_hi:[1,1,0]
	v_pk_fma_f32 v[150:151], v[150:151], s[40:41], 1.0 op_sel_hi:[1,1,0]
	v_pk_mul_f32 v[142:143], v[142:143], s[42:43]
	v_pk_mul_f32 v[150:151], v[150:151], s[42:43]
	v_pk_mul_f32 v[142:143], v[142:143], v[96:97]
	v_pk_mul_f32 v[150:151], v[150:151], v[98:99]
	v_exp_f32_e32 v142, v142
	v_exp_f32_e32 v143, v143
	v_exp_f32_e32 v150, v150
	v_exp_f32_e32 v151, v151
	v_pk_add_f32 v[142:143], v[142:143], 1.0 op_sel_hi:[1,0]
	v_pk_add_f32 v[150:151], v[150:151], 1.0 op_sel_hi:[1,0]
	v_rcp_f32_e32 v142, v142
	v_rcp_f32_e32 v143, v143
	v_rcp_f32_e32 v150, v150
	v_rcp_f32_e32 v151, v151
	v_pk_mul_f32 v[96:97], v[96:97], v[142:143]
	v_pk_mul_f32 v[98:99], v[98:99], v[150:151]
	v_cvt_pk_bf16_f32 v100, v100, v101
	v_cvt_pk_bf16_f32 v101, v102, v103
	v_cvt_pk_bf16_f32 v102, v96, v97
	v_cvt_pk_bf16_f32 v103, v98, v99
	s_nop 1
	v_permlane16_swap_b32_e32 v100, v102
	v_permlane16_swap_b32_e32 v101, v103
	global_store_dwordx4 v149, v[100:103], s[34:35] offset:256
	v_add_u32_e32 v149, 0x8000, v152
	v_pk_mul_f32 v[142:143], v[92:93], v[92:93]
	v_pk_mul_f32 v[150:151], v[94:95], v[94:95]
	v_pk_fma_f32 v[142:143], v[142:143], s[40:41], 1.0 op_sel_hi:[1,1,0]
	v_pk_fma_f32 v[150:151], v[150:151], s[40:41], 1.0 op_sel_hi:[1,1,0]
	v_pk_mul_f32 v[142:143], v[142:143], s[42:43]
	v_pk_mul_f32 v[150:151], v[150:151], s[42:43]
	v_pk_mul_f32 v[142:143], v[142:143], v[92:93]
	v_pk_mul_f32 v[150:151], v[150:151], v[94:95]
	v_exp_f32_e32 v142, v142
	v_exp_f32_e32 v143, v143
	v_exp_f32_e32 v150, v150
	v_exp_f32_e32 v151, v151
	v_pk_add_f32 v[142:143], v[142:143], 1.0 op_sel_hi:[1,0]
	v_pk_add_f32 v[150:151], v[150:151], 1.0 op_sel_hi:[1,0]
	v_rcp_f32_e32 v142, v142
	v_rcp_f32_e32 v143, v143
	v_rcp_f32_e32 v150, v150
	v_rcp_f32_e32 v151, v151
	v_pk_mul_f32 v[92:93], v[92:93], v[142:143]
	v_pk_mul_f32 v[94:95], v[94:95], v[150:151]
	v_pk_mul_f32 v[142:143], v[88:89], v[88:89]
	v_pk_mul_f32 v[150:151], v[90:91], v[90:91]
	v_pk_fma_f32 v[142:143], v[142:143], s[40:41], 1.0 op_sel_hi:[1,1,0]
	v_pk_fma_f32 v[150:151], v[150:151], s[40:41], 1.0 op_sel_hi:[1,1,0]
	v_pk_mul_f32 v[142:143], v[142:143], s[42:43]
	v_pk_mul_f32 v[150:151], v[150:151], s[42:43]
	v_pk_mul_f32 v[142:143], v[142:143], v[88:89]
	v_pk_mul_f32 v[150:151], v[150:151], v[90:91]
	v_exp_f32_e32 v142, v142
	v_exp_f32_e32 v143, v143
	v_exp_f32_e32 v150, v150
	v_exp_f32_e32 v151, v151
	v_pk_add_f32 v[142:143], v[142:143], 1.0 op_sel_hi:[1,0]
	v_pk_add_f32 v[150:151], v[150:151], 1.0 op_sel_hi:[1,0]
	v_rcp_f32_e32 v142, v142
	v_rcp_f32_e32 v143, v143
	v_rcp_f32_e32 v150, v150
	v_rcp_f32_e32 v151, v151
	v_pk_mul_f32 v[88:89], v[88:89], v[142:143]
	v_pk_mul_f32 v[90:91], v[90:91], v[150:151]
	v_cvt_pk_bf16_f32 v92, v92, v93
	v_cvt_pk_bf16_f32 v93, v94, v95
	v_cvt_pk_bf16_f32 v94, v88, v89
	v_cvt_pk_bf16_f32 v95, v90, v91
	s_nop 1
	v_permlane16_swap_b32_e32 v92, v94
	v_permlane16_swap_b32_e32 v93, v95
	global_store_dwordx4 v149, v[92:95], s[34:35]
	v_pk_mul_f32 v[142:143], v[84:85], v[84:85]
	v_pk_mul_f32 v[150:151], v[86:87], v[86:87]
	v_pk_fma_f32 v[142:143], v[142:143], s[40:41], 1.0 op_sel_hi:[1,1,0]
	v_pk_fma_f32 v[150:151], v[150:151], s[40:41], 1.0 op_sel_hi:[1,1,0]
	v_pk_mul_f32 v[142:143], v[142:143], s[42:43]
	v_pk_mul_f32 v[150:151], v[150:151], s[42:43]
	v_pk_mul_f32 v[142:143], v[142:143], v[84:85]
	v_pk_mul_f32 v[150:151], v[150:151], v[86:87]
	v_exp_f32_e32 v142, v142
	v_exp_f32_e32 v143, v143
	v_exp_f32_e32 v150, v150
	v_exp_f32_e32 v151, v151
	v_pk_add_f32 v[142:143], v[142:143], 1.0 op_sel_hi:[1,0]
	v_pk_add_f32 v[150:151], v[150:151], 1.0 op_sel_hi:[1,0]
; __device__ __forceinline__ unsigned cvt_pk_bf16(float lo, float hi) { unsigned r; asm("v_cvt_pk_bf16_f32 %0, %1, %2" : "=v"(r) : "v"(lo), "v"(hi)); return r; }
; __device__ __forceinline__ float gelu_tanh(float x) { const float u = 0.7978845608028654f * (x + 0.044715f * x * x * x); return x * fast_sigmoid(2.0f * u); }
; __device__ __forceinline__ float fast_sigmoid(float x) { return __builtin_amdgcn_rcpf(1.0f + __builtin_amdgcn_exp2f(-x * LOG2E)); }
;     __device__ __forceinline__ void operator()(const Acc& acc, const Unit& u, int wr, int wc, int fr, int fq) const {
;     ...
;             for (int m = 0; m < 4; ++m) { const int nrow = pml * 256 + ai * 128 + wr * 64 + m * 16 + fr;
; #pragma unroll
;                 for (int bj = 0; bj < 2; ++bj)
; #pragma unroll
;                     for (int n = 0; n < 2; ++n) { const int t = pnl * 16 + bj * 8 + wc * 2 + n; const f32x4 a = acc[ai][bj][m][n];
;                         u32x2 w; w.x = cvt_pk_bf16(gelu_tanh(a[0]), gelu_tanh(a[1])); w.y = cvt_pk_bf16(gelu_tanh(a[2]), gelu_tanh(a[3]));
;                         *(u32x2*)(G + ((size_t)g * MX + nrow * 32 + t) * 16 + 4 * fq) = w; } }
	v_rcp_f32_e32 v142, v142
	v_rcp_f32_e32 v143, v143
	v_rcp_f32_e32 v150, v150
	v_rcp_f32_e32 v151, v151
	v_pk_mul_f32 v[84:85], v[84:85], v[142:143]
	v_pk_mul_f32 v[86:87], v[86:87], v[150:151]
	v_pk_mul_f32 v[142:143], v[80:81], v[80:81]
	v_pk_mul_f32 v[150:151], v[82:83], v[82:83]
	v_pk_fma_f32 v[142:143], v[142:143], s[40:41], 1.0 op_sel_hi:[1,1,0]
	v_pk_fma_f32 v[150:151], v[150:151], s[40:41], 1.0 op_sel_hi:[1,1,0]
	v_pk_mul_f32 v[142:143], v[142:143], s[42:43]
	v_pk_mul_f32 v[150:151], v[150:151], s[42:43]
	v_pk_mul_f32 v[142:143], v[142:143], v[80:81]
	v_pk_mul_f32 v[150:151], v[150:151], v[82:83]
	v_exp_f32_e32 v142, v142
	v_exp_f32_e32 v143, v143
	v_exp_f32_e32 v150, v150
	v_exp_f32_e32 v151, v151
	v_pk_add_f32 v[142:143], v[142:143], 1.0 op_sel_hi:[1,0]
	v_pk_add_f32 v[150:151], v[150:151], 1.0 op_sel_hi:[1,0]
	v_rcp_f32_e32 v142, v142
	v_rcp_f32_e32 v143, v143
	v_rcp_f32_e32 v150, v150
	v_rcp_f32_e32 v151, v151
	v_pk_mul_f32 v[80:81], v[80:81], v[142:143]
	v_pk_mul_f32 v[82:83], v[82:83], v[150:151]
	v_cvt_pk_bf16_f32 v84, v84, v85
	v_cvt_pk_bf16_f32 v85, v86, v87
	v_cvt_pk_bf16_f32 v86, v80, v81
	v_cvt_pk_bf16_f32 v87, v82, v83
	s_nop 1
	v_permlane16_swap_b32_e32 v84, v86
	v_permlane16_swap_b32_e32 v85, v87
	global_store_dwordx4 v149, v[84:87], s[34:35] offset:256
	v_add_u32_e32 v149, 0xc000, v152
	v_pk_mul_f32 v[142:143], v[76:77], v[76:77]
	v_pk_mul_f32 v[150:151], v[78:79], v[78:79]
	v_pk_fma_f32 v[142:143], v[142:143], s[40:41], 1.0 op_sel_hi:[1,1,0]
	v_pk_fma_f32 v[150:151], v[150:151], s[40:41], 1.0 op_sel_hi:[1,1,0]
	v_pk_mul_f32 v[142:143], v[142:143], s[42:43]
	v_pk_mul_f32 v[150:151], v[150:151], s[42:43]
	v_pk_mul_f32 v[142:143], v[142:143], v[76:77]
	v_pk_mul_f32 v[150:151], v[150:151], v[78:79]
	v_exp_f32_e32 v142, v142
	v_exp_f32_e32 v143, v143
	v_exp_f32_e32 v150, v150
	v_exp_f32_e32 v151, v151
	v_pk_add_f32 v[142:143], v[142:143], 1.0 op_sel_hi:[1,0]
	v_pk_add_f32 v[150:151], v[150:151], 1.0 op_sel_hi:[1,0]
	v_rcp_f32_e32 v142, v142
	v_rcp_f32_e32 v143, v143
	v_rcp_f32_e32 v150, v150
	v_rcp_f32_e32 v151, v151
	v_pk_mul_f32 v[76:77], v[76:77], v[142:143]
	v_pk_mul_f32 v[78:79], v[78:79], v[150:151]
	v_pk_mul_f32 v[142:143], v[72:73], v[72:73]
	v_pk_mul_f32 v[150:151], v[74:75], v[74:75]
	v_pk_fma_f32 v[142:143], v[142:143], s[40:41], 1.0 op_sel_hi:[1,1,0]
	v_pk_fma_f32 v[150:151], v[150:151], s[40:41], 1.0 op_sel_hi:[1,1,0]
	v_pk_mul_f32 v[142:143], v[142:143], s[42:43]
	v_pk_mul_f32 v[150:151], v[150:151], s[42:43]
	v_pk_mul_f32 v[142:143], v[142:143], v[72:73]
	v_pk_mul_f32 v[150:151], v[150:151], v[74:75]
	v_exp_f32_e32 v142, v142
	v_exp_f32_e32 v143, v143
	v_exp_f32_e32 v150, v150
	v_exp_f32_e32 v151, v151
	v_pk_add_f32 v[142:143], v[142:143], 1.0 op_sel_hi:[1,0]
	v_pk_add_f32 v[150:151], v[150:151], 1.0 op_sel_hi:[1,0]
	v_rcp_f32_e32 v142, v142
	v_rcp_f32_e32 v143, v143
	v_rcp_f32_e32 v150, v150
	v_rcp_f32_e32 v151, v151
	v_pk_mul_f32 v[72:73], v[72:73], v[142:143]
	v_pk_mul_f32 v[74:75], v[74:75], v[150:151]
	v_cvt_pk_bf16_f32 v76, v76, v77
	v_cvt_pk_bf16_f32 v77, v78, v79
	v_cvt_pk_bf16_f32 v78, v72, v73
	v_cvt_pk_bf16_f32 v79, v74, v75
	s_nop 1
	v_permlane16_swap_b32_e32 v76, v78
	v_permlane16_swap_b32_e32 v77, v79
	global_store_dwordx4 v149, v[76:79], s[34:35]
	v_pk_mul_f32 v[142:143], v[68:69], v[68:69]
	v_pk_mul_f32 v[150:151], v[70:71], v[70:71]
	v_pk_fma_f32 v[142:143], v[142:143], s[40:41], 1.0 op_sel_hi:[1,1,0]
	v_pk_fma_f32 v[150:151], v[150:151], s[40:41], 1.0 op_sel_hi:[1,1,0]
	v_pk_mul_f32 v[142:143], v[142:143], s[42:43]
	v_pk_mul_f32 v[150:151], v[150:151], s[42:43]
	v_pk_mul_f32 v[142:143], v[142:143], v[68:69]
	v_pk_mul_f32 v[150:151], v[150:151], v[70:71]
	v_exp_f32_e32 v142, v142
	v_exp_f32_e32 v143, v143
	v_exp_f32_e32 v150, v150
	v_exp_f32_e32 v151, v151
	v_pk_add_f32 v[142:143], v[142:143], 1.0 op_sel_hi:[1,0]
	v_pk_add_f32 v[150:151], v[150:151], 1.0 op_sel_hi:[1,0]
	v_rcp_f32_e32 v142, v142
	v_rcp_f32_e32 v143, v143
	v_rcp_f32_e32 v150, v150
	v_rcp_f32_e32 v151, v151
	v_pk_mul_f32 v[68:69], v[68:69], v[142:143]
	v_pk_mul_f32 v[70:71], v[70:71], v[150:151]
	v_pk_mul_f32 v[142:143], v[64:65], v[64:65]
	v_pk_mul_f32 v[150:151], v[66:67], v[66:67]
	v_pk_fma_f32 v[142:143], v[142:143], s[40:41], 1.0 op_sel_hi:[1,1,0]
	v_pk_fma_f32 v[150:151], v[150:151], s[40:41], 1.0 op_sel_hi:[1,1,0]
	v_pk_mul_f32 v[142:143], v[142:143], s[42:43]
	v_pk_mul_f32 v[150:151], v[150:151], s[42:43]
	v_pk_mul_f32 v[142:143], v[142:143], v[64:65]
	v_pk_mul_f32 v[150:151], v[150:151], v[66:67]
	v_exp_f32_e32 v142, v142
	v_exp_f32_e32 v143, v143
	v_exp_f32_e32 v150, v150
	v_exp_f32_e32 v151, v151
	v_pk_add_f32 v[142:143], v[142:143], 1.0 op_sel_hi:[1,0]
	v_pk_add_f32 v[150:151], v[150:151], 1.0 op_sel_hi:[1,0]
	v_rcp_f32_e32 v142, v142
	v_rcp_f32_e32 v143, v143
	v_rcp_f32_e32 v150, v150
	v_rcp_f32_e32 v151, v151
	v_pk_mul_f32 v[64:65], v[64:65], v[142:143]
	v_pk_mul_f32 v[66:67], v[66:67], v[150:151]
	v_cvt_pk_bf16_f32 v68, v68, v69
	v_cvt_pk_bf16_f32 v69, v70, v71
	v_cvt_pk_bf16_f32 v70, v64, v65
	v_cvt_pk_bf16_f32 v71, v66, v67
	s_nop 1
	v_permlane16_swap_b32_e32 v68, v70
	v_permlane16_swap_b32_e32 v69, v71
	global_store_dwordx4 v149, v[68:71], s[34:35] offset:256
	v_add_u32_e32 v149, 0x20000, v152
	v_pk_mul_f32 v[142:143], v[60:61], v[60:61]
	v_pk_mul_f32 v[150:151], v[62:63], v[62:63]
	v_pk_fma_f32 v[142:143], v[142:143], s[40:41], 1.0 op_sel_hi:[1,1,0]
	v_pk_fma_f32 v[150:151], v[150:151], s[40:41], 1.0 op_sel_hi:[1,1,0]
	v_pk_mul_f32 v[142:143], v[142:143], s[42:43]
	v_pk_mul_f32 v[150:151], v[150:151], s[42:43]
	v_pk_mul_f32 v[142:143], v[142:143], v[60:61]
	v_pk_mul_f32 v[150:151], v[150:151], v[62:63]
; __device__ __forceinline__ unsigned cvt_pk_bf16(float lo, float hi) { unsigned r; asm("v_cvt_pk_bf16_f32 %0, %1, %2" : "=v"(r) : "v"(lo), "v"(hi)); return r; }
; __device__ __forceinline__ float gelu_tanh(float x) { const float u = 0.7978845608028654f * (x + 0.044715f * x * x * x); return x * fast_sigmoid(2.0f * u); }
; __device__ __forceinline__ float fast_sigmoid(float x) { return __builtin_amdgcn_rcpf(1.0f + __builtin_amdgcn_exp2f(-x * LOG2E)); }
;     __device__ __forceinline__ void operator()(const Acc& acc, const Unit& u, int wr, int wc, int fr, int fq) const {
;     ...
;             for (int m = 0; m < 4; ++m) { const int nrow = pml * 256 + ai * 128 + wr * 64 + m * 16 + fr;
; #pragma unroll
;                 for (int bj = 0; bj < 2; ++bj)
; #pragma unroll
;                     for (int n = 0; n < 2; ++n) { const int t = pnl * 16 + bj * 8 + wc * 2 + n; const f32x4 a = acc[ai][bj][m][n];
;                         u32x2 w; w.x = cvt_pk_bf16(gelu_tanh(a[0]), gelu_tanh(a[1])); w.y = cvt_pk_bf16(gelu_tanh(a[2]), gelu_tanh(a[3]));
;                         *(u32x2*)(G + ((size_t)g * MX + nrow * 32 + t) * 16 + 4 * fq) = w; } }
	v_exp_f32_e32 v142, v142
	v_exp_f32_e32 v143, v143
	v_exp_f32_e32 v150, v150
	v_exp_f32_e32 v151, v151
	v_pk_add_f32 v[142:143], v[142:143], 1.0 op_sel_hi:[1,0]
	v_pk_add_f32 v[150:151], v[150:151], 1.0 op_sel_hi:[1,0]
	v_rcp_f32_e32 v142, v142
	v_rcp_f32_e32 v143, v143
	v_rcp_f32_e32 v150, v150
	v_rcp_f32_e32 v151, v151
	v_pk_mul_f32 v[60:61], v[60:61], v[142:143]
	v_pk_mul_f32 v[62:63], v[62:63], v[150:151]
	v_pk_mul_f32 v[142:143], v[56:57], v[56:57]
	v_pk_mul_f32 v[150:151], v[58:59], v[58:59]
	v_pk_fma_f32 v[142:143], v[142:143], s[40:41], 1.0 op_sel_hi:[1,1,0]
	v_pk_fma_f32 v[150:151], v[150:151], s[40:41], 1.0 op_sel_hi:[1,1,0]
	v_pk_mul_f32 v[142:143], v[142:143], s[42:43]
	v_pk_mul_f32 v[150:151], v[150:151], s[42:43]
	v_pk_mul_f32 v[142:143], v[142:143], v[56:57]
	v_pk_mul_f32 v[150:151], v[150:151], v[58:59]
	v_exp_f32_e32 v142, v142
	v_exp_f32_e32 v143, v143
	v_exp_f32_e32 v150, v150
	v_exp_f32_e32 v151, v151
	v_pk_add_f32 v[142:143], v[142:143], 1.0 op_sel_hi:[1,0]
	v_pk_add_f32 v[150:151], v[150:151], 1.0 op_sel_hi:[1,0]
	v_rcp_f32_e32 v142, v142
	v_rcp_f32_e32 v143, v143
	v_rcp_f32_e32 v150, v150
	v_rcp_f32_e32 v151, v151
	v_pk_mul_f32 v[56:57], v[56:57], v[142:143]
	v_pk_mul_f32 v[58:59], v[58:59], v[150:151]
	v_cvt_pk_bf16_f32 v60, v60, v61
	v_cvt_pk_bf16_f32 v61, v62, v63
	v_cvt_pk_bf16_f32 v62, v56, v57
	v_cvt_pk_bf16_f32 v63, v58, v59
	s_nop 1
	v_permlane16_swap_b32_e32 v60, v62
	v_permlane16_swap_b32_e32 v61, v63
	global_store_dwordx4 v149, v[60:63], s[34:35]
	v_pk_mul_f32 v[142:143], v[52:53], v[52:53]
	v_pk_mul_f32 v[150:151], v[54:55], v[54:55]
	v_pk_fma_f32 v[142:143], v[142:143], s[40:41], 1.0 op_sel_hi:[1,1,0]
	v_pk_fma_f32 v[150:151], v[150:151], s[40:41], 1.0 op_sel_hi:[1,1,0]
	v_pk_mul_f32 v[142:143], v[142:143], s[42:43]
	v_pk_mul_f32 v[150:151], v[150:151], s[42:43]
	v_pk_mul_f32 v[142:143], v[142:143], v[52:53]
	v_pk_mul_f32 v[150:151], v[150:151], v[54:55]
	v_exp_f32_e32 v142, v142
	v_exp_f32_e32 v143, v143
	v_exp_f32_e32 v150, v150
	v_exp_f32_e32 v151, v151
	v_pk_add_f32 v[142:143], v[142:143], 1.0 op_sel_hi:[1,0]
	v_pk_add_f32 v[150:151], v[150:151], 1.0 op_sel_hi:[1,0]
	v_rcp_f32_e32 v142, v142
	v_rcp_f32_e32 v143, v143
	v_rcp_f32_e32 v150, v150
	v_rcp_f32_e32 v151, v151
	v_pk_mul_f32 v[52:53], v[52:53], v[142:143]
	v_pk_mul_f32 v[54:55], v[54:55], v[150:151]
	v_pk_mul_f32 v[142:143], v[48:49], v[48:49]
	v_pk_mul_f32 v[150:151], v[50:51], v[50:51]
	v_pk_fma_f32 v[142:143], v[142:143], s[40:41], 1.0 op_sel_hi:[1,1,0]
	v_pk_fma_f32 v[150:151], v[150:151], s[40:41], 1.0 op_sel_hi:[1,1,0]
	v_pk_mul_f32 v[142:143], v[142:143], s[42:43]
	v_pk_mul_f32 v[150:151], v[150:151], s[42:43]
	v_pk_mul_f32 v[142:143], v[142:143], v[48:49]
	v_pk_mul_f32 v[150:151], v[150:151], v[50:51]
	v_exp_f32_e32 v142, v142
	v_exp_f32_e32 v143, v143
	v_exp_f32_e32 v150, v150
	v_exp_f32_e32 v151, v151
	v_pk_add_f32 v[142:143], v[142:143], 1.0 op_sel_hi:[1,0]
	v_pk_add_f32 v[150:151], v[150:151], 1.0 op_sel_hi:[1,0]
	v_rcp_f32_e32 v142, v142
	v_rcp_f32_e32 v143, v143
	v_rcp_f32_e32 v150, v150
	v_rcp_f32_e32 v151, v151
	v_pk_mul_f32 v[48:49], v[48:49], v[142:143]
	v_pk_mul_f32 v[50:51], v[50:51], v[150:151]
	v_cvt_pk_bf16_f32 v52, v52, v53
	v_cvt_pk_bf16_f32 v53, v54, v55
	v_cvt_pk_bf16_f32 v54, v48, v49
	v_cvt_pk_bf16_f32 v55, v50, v51
	s_nop 1
	v_permlane16_swap_b32_e32 v52, v54
	v_permlane16_swap_b32_e32 v53, v55
	global_store_dwordx4 v149, v[52:55], s[34:35] offset:256
	v_add_u32_e32 v149, 0x24000, v152
	v_pk_mul_f32 v[142:143], v[44:45], v[44:45]
	v_pk_mul_f32 v[150:151], v[46:47], v[46:47]
	v_pk_fma_f32 v[142:143], v[142:143], s[40:41], 1.0 op_sel_hi:[1,1,0]
	v_pk_fma_f32 v[150:151], v[150:151], s[40:41], 1.0 op_sel_hi:[1,1,0]
	v_pk_mul_f32 v[142:143], v[142:143], s[42:43]
	v_pk_mul_f32 v[150:151], v[150:151], s[42:43]
	v_pk_mul_f32 v[142:143], v[142:143], v[44:45]
	v_pk_mul_f32 v[150:151], v[150:151], v[46:47]
	v_exp_f32_e32 v142, v142
	v_exp_f32_e32 v143, v143
	v_exp_f32_e32 v150, v150
	v_exp_f32_e32 v151, v151
	v_pk_add_f32 v[142:143], v[142:143], 1.0 op_sel_hi:[1,0]
	v_pk_add_f32 v[150:151], v[150:151], 1.0 op_sel_hi:[1,0]
	v_rcp_f32_e32 v142, v142
	v_rcp_f32_e32 v143, v143
	v_rcp_f32_e32 v150, v150
	v_rcp_f32_e32 v151, v151
	v_pk_mul_f32 v[44:45], v[44:45], v[142:143]
	v_pk_mul_f32 v[46:47], v[46:47], v[150:151]
	v_pk_mul_f32 v[142:143], v[40:41], v[40:41]
	v_pk_mul_f32 v[150:151], v[42:43], v[42:43]
	v_pk_fma_f32 v[142:143], v[142:143], s[40:41], 1.0 op_sel_hi:[1,1,0]
	v_pk_fma_f32 v[150:151], v[150:151], s[40:41], 1.0 op_sel_hi:[1,1,0]
	v_pk_mul_f32 v[142:143], v[142:143], s[42:43]
	v_pk_mul_f32 v[150:151], v[150:151], s[42:43]
	v_pk_mul_f32 v[142:143], v[142:143], v[40:41]
	v_pk_mul_f32 v[150:151], v[150:151], v[42:43]
	v_exp_f32_e32 v142, v142
	v_exp_f32_e32 v143, v143
	v_exp_f32_e32 v150, v150
	v_exp_f32_e32 v151, v151
	v_pk_add_f32 v[142:143], v[142:143], 1.0 op_sel_hi:[1,0]
	v_pk_add_f32 v[150:151], v[150:151], 1.0 op_sel_hi:[1,0]
	v_rcp_f32_e32 v142, v142
	v_rcp_f32_e32 v143, v143
	v_rcp_f32_e32 v150, v150
	v_rcp_f32_e32 v151, v151
	v_pk_mul_f32 v[40:41], v[40:41], v[142:143]
	v_pk_mul_f32 v[42:43], v[42:43], v[150:151]
	v_cvt_pk_bf16_f32 v44, v44, v45
	v_cvt_pk_bf16_f32 v45, v46, v47
	v_cvt_pk_bf16_f32 v46, v40, v41
	v_cvt_pk_bf16_f32 v47, v42, v43
	s_nop 1
	v_permlane16_swap_b32_e32 v44, v46
	v_permlane16_swap_b32_e32 v45, v47
	global_store_dwordx4 v149, v[44:47], s[34:35]
	v_pk_mul_f32 v[142:143], v[36:37], v[36:37]
	v_pk_mul_f32 v[150:151], v[38:39], v[38:39]
	v_pk_fma_f32 v[142:143], v[142:143], s[40:41], 1.0 op_sel_hi:[1,1,0]
	v_pk_fma_f32 v[150:151], v[150:151], s[40:41], 1.0 op_sel_hi:[1,1,0]
; __device__ __forceinline__ unsigned cvt_pk_bf16(float lo, float hi) { unsigned r; asm("v_cvt_pk_bf16_f32 %0, %1, %2" : "=v"(r) : "v"(lo), "v"(hi)); return r; }
; __device__ __forceinline__ float gelu_tanh(float x) { const float u = 0.7978845608028654f * (x + 0.044715f * x * x * x); return x * fast_sigmoid(2.0f * u); }
; __device__ __forceinline__ float fast_sigmoid(float x) { return __builtin_amdgcn_rcpf(1.0f + __builtin_amdgcn_exp2f(-x * LOG2E)); }
;     __device__ __forceinline__ void operator()(const Acc& acc, const Unit& u, int wr, int wc, int fr, int fq) const {
;     ...
;             for (int m = 0; m < 4; ++m) { const int nrow = pml * 256 + ai * 128 + wr * 64 + m * 16 + fr;
; #pragma unroll
;                 for (int bj = 0; bj < 2; ++bj)
; #pragma unroll
;                     for (int n = 0; n < 2; ++n) { const int t = pnl * 16 + bj * 8 + wc * 2 + n; const f32x4 a = acc[ai][bj][m][n];
;                         u32x2 w; w.x = cvt_pk_bf16(gelu_tanh(a[0]), gelu_tanh(a[1])); w.y = cvt_pk_bf16(gelu_tanh(a[2]), gelu_tanh(a[3]));
;                         *(u32x2*)(G + ((size_t)g * MX + nrow * 32 + t) * 16 + 4 * fq) = w; } }
	v_pk_mul_f32 v[142:143], v[142:143], s[42:43]
	v_pk_mul_f32 v[150:151], v[150:151], s[42:43]
	v_pk_mul_f32 v[142:143], v[142:143], v[36:37]
	v_pk_mul_f32 v[150:151], v[150:151], v[38:39]
	v_exp_f32_e32 v142, v142
	v_exp_f32_e32 v143, v143
	v_exp_f32_e32 v150, v150
	v_exp_f32_e32 v151, v151
	v_pk_add_f32 v[142:143], v[142:143], 1.0 op_sel_hi:[1,0]
	v_pk_add_f32 v[150:151], v[150:151], 1.0 op_sel_hi:[1,0]
	v_rcp_f32_e32 v142, v142
	v_rcp_f32_e32 v143, v143
	v_rcp_f32_e32 v150, v150
	v_rcp_f32_e32 v151, v151
	v_pk_mul_f32 v[36:37], v[36:37], v[142:143]
	v_pk_mul_f32 v[38:39], v[38:39], v[150:151]
	v_pk_mul_f32 v[142:143], v[32:33], v[32:33]
	v_pk_mul_f32 v[150:151], v[34:35], v[34:35]
	v_pk_fma_f32 v[142:143], v[142:143], s[40:41], 1.0 op_sel_hi:[1,1,0]
	v_pk_fma_f32 v[150:151], v[150:151], s[40:41], 1.0 op_sel_hi:[1,1,0]
	v_pk_mul_f32 v[142:143], v[142:143], s[42:43]
	v_pk_mul_f32 v[150:151], v[150:151], s[42:43]
	v_pk_mul_f32 v[142:143], v[142:143], v[32:33]
	v_pk_mul_f32 v[150:151], v[150:151], v[34:35]
	v_exp_f32_e32 v142, v142
	v_exp_f32_e32 v143, v143
	v_exp_f32_e32 v150, v150
	v_exp_f32_e32 v151, v151
	v_pk_add_f32 v[142:143], v[142:143], 1.0 op_sel_hi:[1,0]
	v_pk_add_f32 v[150:151], v[150:151], 1.0 op_sel_hi:[1,0]
	v_rcp_f32_e32 v142, v142
	v_rcp_f32_e32 v143, v143
	v_rcp_f32_e32 v150, v150
	v_rcp_f32_e32 v151, v151
	v_pk_mul_f32 v[32:33], v[32:33], v[142:143]
	v_pk_mul_f32 v[34:35], v[34:35], v[150:151]
	v_cvt_pk_bf16_f32 v36, v36, v37
	v_cvt_pk_bf16_f32 v37, v38, v39
	v_cvt_pk_bf16_f32 v38, v32, v33
	v_cvt_pk_bf16_f32 v39, v34, v35
	s_nop 1
	v_permlane16_swap_b32_e32 v36, v38
	v_permlane16_swap_b32_e32 v37, v39
	global_store_dwordx4 v149, v[36:39], s[34:35] offset:256
	v_add_u32_e32 v149, 0x28000, v152
	v_pk_mul_f32 v[142:143], v[28:29], v[28:29]
	v_pk_mul_f32 v[150:151], v[30:31], v[30:31]
	v_pk_fma_f32 v[142:143], v[142:143], s[40:41], 1.0 op_sel_hi:[1,1,0]
	v_pk_fma_f32 v[150:151], v[150:151], s[40:41], 1.0 op_sel_hi:[1,1,0]
	v_pk_mul_f32 v[142:143], v[142:143], s[42:43]
	v_pk_mul_f32 v[150:151], v[150:151], s[42:43]
	v_pk_mul_f32 v[142:143], v[142:143], v[28:29]
	v_pk_mul_f32 v[150:151], v[150:151], v[30:31]
	v_exp_f32_e32 v142, v142
	v_exp_f32_e32 v143, v143
	v_exp_f32_e32 v150, v150
	v_exp_f32_e32 v151, v151
	v_pk_add_f32 v[142:143], v[142:143], 1.0 op_sel_hi:[1,0]
	v_pk_add_f32 v[150:151], v[150:151], 1.0 op_sel_hi:[1,0]
	v_rcp_f32_e32 v142, v142
	v_rcp_f32_e32 v143, v143
	v_rcp_f32_e32 v150, v150
	v_rcp_f32_e32 v151, v151
	v_pk_mul_f32 v[28:29], v[28:29], v[142:143]
	v_pk_mul_f32 v[30:31], v[30:31], v[150:151]
	v_pk_mul_f32 v[142:143], v[24:25], v[24:25]
	v_pk_mul_f32 v[150:151], v[26:27], v[26:27]
	v_pk_fma_f32 v[142:143], v[142:143], s[40:41], 1.0 op_sel_hi:[1,1,0]
	v_pk_fma_f32 v[150:151], v[150:151], s[40:41], 1.0 op_sel_hi:[1,1,0]
	v_pk_mul_f32 v[142:143], v[142:143], s[42:43]
	v_pk_mul_f32 v[150:151], v[150:151], s[42:43]
	v_pk_mul_f32 v[142:143], v[142:143], v[24:25]
	v_pk_mul_f32 v[150:151], v[150:151], v[26:27]
	v_exp_f32_e32 v142, v142
	v_exp_f32_e32 v143, v143
	v_exp_f32_e32 v150, v150
	v_exp_f32_e32 v151, v151
	v_pk_add_f32 v[142:143], v[142:143], 1.0 op_sel_hi:[1,0]
	v_pk_add_f32 v[150:151], v[150:151], 1.0 op_sel_hi:[1,0]
	v_rcp_f32_e32 v142, v142
	v_rcp_f32_e32 v143, v143
	v_rcp_f32_e32 v150, v150
	v_rcp_f32_e32 v151, v151
	v_pk_mul_f32 v[24:25], v[24:25], v[142:143]
	v_pk_mul_f32 v[26:27], v[26:27], v[150:151]
	v_cvt_pk_bf16_f32 v28, v28, v29
	v_cvt_pk_bf16_f32 v29, v30, v31
	v_cvt_pk_bf16_f32 v30, v24, v25
	v_cvt_pk_bf16_f32 v31, v26, v27
	s_nop 1
	v_permlane16_swap_b32_e32 v28, v30
	v_permlane16_swap_b32_e32 v29, v31
	global_store_dwordx4 v149, v[28:31], s[34:35]
	v_pk_mul_f32 v[142:143], v[20:21], v[20:21]
	v_pk_mul_f32 v[150:151], v[22:23], v[22:23]
	v_pk_fma_f32 v[142:143], v[142:143], s[40:41], 1.0 op_sel_hi:[1,1,0]
	v_pk_fma_f32 v[150:151], v[150:151], s[40:41], 1.0 op_sel_hi:[1,1,0]
	v_pk_mul_f32 v[142:143], v[142:143], s[42:43]
	v_pk_mul_f32 v[150:151], v[150:151], s[42:43]
	v_pk_mul_f32 v[142:143], v[142:143], v[20:21]
	v_pk_mul_f32 v[150:151], v[150:151], v[22:23]
	v_exp_f32_e32 v142, v142
	v_exp_f32_e32 v143, v143
	v_exp_f32_e32 v150, v150
	v_exp_f32_e32 v151, v151
	v_pk_add_f32 v[142:143], v[142:143], 1.0 op_sel_hi:[1,0]
	v_pk_add_f32 v[150:151], v[150:151], 1.0 op_sel_hi:[1,0]
	v_rcp_f32_e32 v142, v142
	v_rcp_f32_e32 v143, v143
	v_rcp_f32_e32 v150, v150
	v_rcp_f32_e32 v151, v151
	v_pk_mul_f32 v[20:21], v[20:21], v[142:143]
	v_pk_mul_f32 v[22:23], v[22:23], v[150:151]
	v_pk_mul_f32 v[142:143], v[16:17], v[16:17]
	v_pk_mul_f32 v[150:151], v[18:19], v[18:19]
	v_pk_fma_f32 v[142:143], v[142:143], s[40:41], 1.0 op_sel_hi:[1,1,0]
	v_pk_fma_f32 v[150:151], v[150:151], s[40:41], 1.0 op_sel_hi:[1,1,0]
	v_pk_mul_f32 v[142:143], v[142:143], s[42:43]
	v_pk_mul_f32 v[150:151], v[150:151], s[42:43]
; __device__ __forceinline__ unsigned cvt_pk_bf16(float lo, float hi) { unsigned r; asm("v_cvt_pk_bf16_f32 %0, %1, %2" : "=v"(r) : "v"(lo), "v"(hi)); return r; }
; __device__ __forceinline__ float gelu_tanh(float x) { const float u = 0.7978845608028654f * (x + 0.044715f * x * x * x); return x * fast_sigmoid(2.0f * u); }
; __device__ __forceinline__ float fast_sigmoid(float x) { return __builtin_amdgcn_rcpf(1.0f + __builtin_amdgcn_exp2f(-x * LOG2E)); }
;     __device__ __forceinline__ void operator()(const Acc& acc, const Unit& u, int wr, int wc, int fr, int fq) const {
;     ...
;             for (int m = 0; m < 4; ++m) { const int nrow = pml * 256 + ai * 128 + wr * 64 + m * 16 + fr;
; #pragma unroll
;                 for (int bj = 0; bj < 2; ++bj)
; #pragma unroll
;                     for (int n = 0; n < 2; ++n) { const int t = pnl * 16 + bj * 8 + wc * 2 + n; const f32x4 a = acc[ai][bj][m][n];
;                         u32x2 w; w.x = cvt_pk_bf16(gelu_tanh(a[0]), gelu_tanh(a[1])); w.y = cvt_pk_bf16(gelu_tanh(a[2]), gelu_tanh(a[3]));
;                         *(u32x2*)(G + ((size_t)g * MX + nrow * 32 + t) * 16 + 4 * fq) = w; } }
	v_pk_mul_f32 v[142:143], v[142:143], v[16:17]
	v_pk_mul_f32 v[150:151], v[150:151], v[18:19]
	v_exp_f32_e32 v142, v142
	v_exp_f32_e32 v143, v143
	v_exp_f32_e32 v150, v150
	v_exp_f32_e32 v151, v151
	v_pk_add_f32 v[142:143], v[142:143], 1.0 op_sel_hi:[1,0]
	v_pk_add_f32 v[150:151], v[150:151], 1.0 op_sel_hi:[1,0]
	v_rcp_f32_e32 v142, v142
	v_rcp_f32_e32 v143, v143
	v_rcp_f32_e32 v150, v150
	v_rcp_f32_e32 v151, v151
	v_pk_mul_f32 v[16:17], v[16:17], v[142:143]
	v_pk_mul_f32 v[18:19], v[18:19], v[150:151]
	v_cvt_pk_bf16_f32 v20, v20, v21
	v_cvt_pk_bf16_f32 v21, v22, v23
	v_cvt_pk_bf16_f32 v22, v16, v17
	v_cvt_pk_bf16_f32 v23, v18, v19
	s_nop 1
	v_permlane16_swap_b32_e32 v20, v22
	v_permlane16_swap_b32_e32 v21, v23
	global_store_dwordx4 v149, v[20:23], s[34:35] offset:256
	v_add_u32_e32 v149, 0x2c000, v152
	v_pk_mul_f32 v[142:143], v[12:13], v[12:13]
	v_pk_mul_f32 v[150:151], v[14:15], v[14:15]
	v_pk_fma_f32 v[142:143], v[142:143], s[40:41], 1.0 op_sel_hi:[1,1,0]
	v_pk_fma_f32 v[150:151], v[150:151], s[40:41], 1.0 op_sel_hi:[1,1,0]
	v_pk_mul_f32 v[142:143], v[142:143], s[42:43]
	v_pk_mul_f32 v[150:151], v[150:151], s[42:43]
	v_pk_mul_f32 v[142:143], v[142:143], v[12:13]
	v_pk_mul_f32 v[150:151], v[150:151], v[14:15]
	v_exp_f32_e32 v142, v142
	v_exp_f32_e32 v143, v143
	v_exp_f32_e32 v150, v150
	v_exp_f32_e32 v151, v151
	v_pk_add_f32 v[142:143], v[142:143], 1.0 op_sel_hi:[1,0]
	v_pk_add_f32 v[150:151], v[150:151], 1.0 op_sel_hi:[1,0]
	v_rcp_f32_e32 v142, v142
	v_rcp_f32_e32 v143, v143
	v_rcp_f32_e32 v150, v150
	v_rcp_f32_e32 v151, v151
	v_pk_mul_f32 v[12:13], v[12:13], v[142:143]
	v_pk_mul_f32 v[14:15], v[14:15], v[150:151]
	v_pk_mul_f32 v[142:143], v[8:9], v[8:9]
	v_pk_mul_f32 v[150:151], v[10:11], v[10:11]
	v_pk_fma_f32 v[142:143], v[142:143], s[40:41], 1.0 op_sel_hi:[1,1,0]
	v_pk_fma_f32 v[150:151], v[150:151], s[40:41], 1.0 op_sel_hi:[1,1,0]
	v_pk_mul_f32 v[142:143], v[142:143], s[42:43]
	v_pk_mul_f32 v[150:151], v[150:151], s[42:43]
	v_pk_mul_f32 v[142:143], v[142:143], v[8:9]
	v_pk_mul_f32 v[150:151], v[150:151], v[10:11]
	v_exp_f32_e32 v142, v142
	v_exp_f32_e32 v143, v143
	v_exp_f32_e32 v150, v150
	v_exp_f32_e32 v151, v151
	v_pk_add_f32 v[142:143], v[142:143], 1.0 op_sel_hi:[1,0]
	v_pk_add_f32 v[150:151], v[150:151], 1.0 op_sel_hi:[1,0]
	v_rcp_f32_e32 v142, v142
	v_rcp_f32_e32 v143, v143
	v_rcp_f32_e32 v150, v150
	v_rcp_f32_e32 v151, v151
	v_pk_mul_f32 v[8:9], v[8:9], v[142:143]
	v_pk_mul_f32 v[10:11], v[10:11], v[150:151]
	v_cvt_pk_bf16_f32 v12, v12, v13
	v_cvt_pk_bf16_f32 v13, v14, v15
	v_cvt_pk_bf16_f32 v14, v8, v9
	v_cvt_pk_bf16_f32 v15, v10, v11
	s_nop 1
	v_permlane16_swap_b32_e32 v12, v14
	v_permlane16_swap_b32_e32 v13, v15
	global_store_dwordx4 v149, v[12:15], s[34:35]
	v_pk_mul_f32 v[142:143], v[4:5], v[4:5]
	v_pk_mul_f32 v[150:151], v[6:7], v[6:7]
	v_pk_fma_f32 v[142:143], v[142:143], s[40:41], 1.0 op_sel_hi:[1,1,0]
	v_pk_fma_f32 v[150:151], v[150:151], s[40:41], 1.0 op_sel_hi:[1,1,0]
	v_pk_mul_f32 v[142:143], v[142:143], s[42:43]
	v_pk_mul_f32 v[150:151], v[150:151], s[42:43]
	v_pk_mul_f32 v[142:143], v[142:143], v[4:5]
	v_pk_mul_f32 v[150:151], v[150:151], v[6:7]
	v_exp_f32_e32 v142, v142
	v_exp_f32_e32 v143, v143
	v_exp_f32_e32 v150, v150
	v_exp_f32_e32 v151, v151
	v_pk_add_f32 v[142:143], v[142:143], 1.0 op_sel_hi:[1,0]
	v_pk_add_f32 v[150:151], v[150:151], 1.0 op_sel_hi:[1,0]
	v_rcp_f32_e32 v142, v142
	v_rcp_f32_e32 v143, v143
	v_rcp_f32_e32 v150, v150
	v_rcp_f32_e32 v151, v151
	v_pk_mul_f32 v[4:5], v[4:5], v[142:143]
	v_pk_mul_f32 v[6:7], v[6:7], v[150:151]
	v_pk_mul_f32 v[142:143], v[0:1], v[0:1]
	v_pk_mul_f32 v[150:151], v[2:3], v[2:3]
	v_pk_fma_f32 v[142:143], v[142:143], s[40:41], 1.0 op_sel_hi:[1,1,0]
	v_pk_fma_f32 v[150:151], v[150:151], s[40:41], 1.0 op_sel_hi:[1,1,0]
	v_pk_mul_f32 v[142:143], v[142:143], s[42:43]
	v_pk_mul_f32 v[150:151], v[150:151], s[42:43]
	v_pk_mul_f32 v[142:143], v[142:143], v[0:1]
	v_pk_mul_f32 v[150:151], v[150:151], v[2:3]
	v_exp_f32_e32 v142, v142
	v_exp_f32_e32 v143, v143
	v_exp_f32_e32 v150, v150
	v_exp_f32_e32 v151, v151
	v_pk_add_f32 v[142:143], v[142:143], 1.0 op_sel_hi:[1,0]
	v_pk_add_f32 v[150:151], v[150:151], 1.0 op_sel_hi:[1,0]
	v_rcp_f32_e32 v142, v142
	v_rcp_f32_e32 v143, v143
	v_rcp_f32_e32 v150, v150
	v_rcp_f32_e32 v151, v151
	v_pk_mul_f32 v[0:1], v[0:1], v[142:143]
	v_pk_mul_f32 v[2:3], v[2:3], v[150:151]
	v_cvt_pk_bf16_f32 v4, v4, v5
	v_cvt_pk_bf16_f32 v5, v6, v7
	v_cvt_pk_bf16_f32 v6, v0, v1
	v_cvt_pk_bf16_f32 v7, v2, v3
	s_nop 1
	v_permlane16_swap_b32_e32 v4, v6
	v_permlane16_swap_b32_e32 v5, v7
	global_store_dwordx4 v149, v[4:7], s[34:35] offset:256
	s_andn2_b64 vcc, exec, s[4:5]
	s_mov_b64 s[4:5], -1
	s_cbranch_vccnz .LBB0_762
	s_andn2_b64 vcc, exec, s[10:11]
	s_cbranch_vccnz .LBB0_761
	s_barrier
	s_branch .LBB0_761
